# stack + K half-tile LDS layout with key bit 3 selecting the 128B half (ds_read_b128 K reads conflict-free)
# speedup vs baseline: 1.0062x; 1.0043x over previous
.LBB0_336:
	v_mov_b32_e32 v52, v162
	v_mov_b32_e32 v123, v99
	v_ashrrev_i32_e32 v50, 4, v52
	v_lshlrev_b32_e32 v20, 3, v52
	v_add_u32_e32 v21, 32, v50
	v_and_b32_e32 v24, 0x78, v20
	v_mad_i64_i32 v[2:3], s[12:13], v50, s52, 0
	v_mad_i64_i32 v[4:5], s[12:13], v21, s52, 0
	v_or_b32_e32 v2, v2, v24
	v_or_b32_e32 v4, v4, v24
	v_lshlrev_b64 v[10:11], 1, v[2:3]
	v_lshlrev_b64 v[12:13], 1, v[4:5]
	v_lshl_add_u64 v[2:3], s[36:37], 0, v[10:11]
	v_lshl_add_u64 v[6:7], s[36:37], 0, v[12:13]
	v_lshl_add_u64 v[10:11], s[34:35], 0, v[10:11]
	v_lshl_add_u64 v[14:15], s[34:35], 0, v[12:13]
	global_load_dwordx4 v[2:5], v[2:3], off
	s_nop 0
	global_load_dwordx4 v[6:9], v[6:7], off
	s_nop 0
	global_load_dwordx4 v[10:13], v[10:11], off
	s_nop 0
	global_load_dwordx4 v[14:17], v[14:15], off
	s_lshl_b32 s12, s8, 7
	s_add_u32 s8, s76, s12
	s_addc_u32 s9, s77, 0
	v_ashrrev_i32_e32 v26, 1, v52
	v_bfe_u32 v51, v52, 5, 1
	v_bfi_b32 v23, s18, v26, v52
	v_mov_b64_e32 v[18:19], s[8:9]
	v_bfe_u32 v27, v20, 5, 2
	v_lshlrev_b32_e32 v28, 5, v50
	v_and_b32_e32 v20, 24, v20
	v_add_u32_e32 v30, 64, v50
	v_lshrrev_b32_e32 v22, 5, v52
	v_lshlrev_b32_e32 v98, 4, v51
	v_add_u32_e32 v31, 0x60, v50
	v_mad_i64_i32 v[18:19], s[8:9], v23, s49, v[18:19]
	v_and_or_b32 v28, v28, s51, v20
	v_lshrrev_b32_e32 v33, 1, v21
	v_lshlrev_b32_e32 v35, 8, v21
	v_mad_i64_i32 v[20:21], s[8:9], v30, s52, 0
	v_and_or_b32 v32, v22, s50, v27
	v_mad_i64_i32 v[22:23], s[8:9], v31, s52, 0
	v_lshl_add_u64 v[18:19], v[18:19], 0, v[98:99]
	v_lshlrev_b32_e32 v28, 1, v28
	v_or_b32_e32 v20, v20, v24
	v_and_b32_e32 v25, 0x70, v52
	v_lshlrev_b32_e32 v29, 8, v50
	v_lshlrev_b32_e32 v34, 1, v24
	v_and_or_b32 v27, v33, s50, v27
	v_or_b32_e32 v22, v22, v24
	global_load_dwordx4 v[118:121], v[18:19], off
	global_load_dwordx4 v[114:117], v[18:19], off offset:32
	global_load_dwordx4 v[110:113], v[18:19], off offset:64
	global_load_dwordx4 v[106:109], v[18:19], off offset:96
	v_lshl_or_b32 v24, v32, 9, v28
	v_lshlrev_b64 v[18:19], 1, v[20:21]
	v_bitop3_b32 v29, v34, v29, v25 bitop3:0xde
	v_bitop3_b32 v25, v34, v35, v25 bitop3:0xde
	v_lshl_or_b32 v27, v27, 9, v28
	v_lshlrev_b64 v[20:21], 1, v[22:23]
	v_add_u32_e32 v183, 0, v24
	v_lshl_add_u64 v[22:23], s[36:37], 0, v[18:19]
	v_add_u32_e32 v181, 0, v29
	v_add_u32_e32 v182, 0, v25
	v_add_u32_e32 v184, 0, v27
	v_lshl_add_u64 v[24:25], s[36:37], 0, v[20:21]
	v_lshl_add_u64 v[18:19], s[34:35], 0, v[18:19]
	v_lshl_add_u64 v[20:21], s[34:35], 0, v[20:21]
	global_load_dwordx4 v[34:37], v[22:23], off
	global_load_dwordx4 v[38:41], v[24:25], off
	global_load_dwordx4 v[42:45], v[18:19], off
	global_load_dwordx4 v[46:49], v[20:21], off
	s_waitcnt vmcnt(0)
	v_and_b32_e32 v55, 63, v52
	v_and_b32_e32 v54, 0xffffffe0, v26
	v_and_b32_e32 v53, 31, v52
	v_add_u32_e32 v185, s75, v54
	v_cmp_gt_u32_e32 vcc, 32, v55
	v_or_b32_e32 v178, v185, v53
	v_mov_b32_e32 v124, v99
	v_cndmask_b32_e32 v122, 0, v170, vcc
	v_mov_b32_e32 v125, v99
	s_barrier
	s_waitcnt vmcnt(7)
	ds_write_b128 v183, v[2:5]
	s_waitcnt vmcnt(6)
	ds_write_b128 v184, v[6:9]
	s_movk_i32 s101, 0x80
	v_lshrrev_b32_e32 v253, 4, v181
	v_bfi_b32 v181, s101, v253, v181
	v_lshrrev_b32_e32 v253, 4, v182
	v_bfi_b32 v182, s101, v253, v182
	v_and_b32_e32 v253, 8, v52
	s_lshr_b32 s100, s12, 4
	v_cmp_eq_u32_e64 s[96:97], s100, v253
	s_waitcnt vmcnt(4)
	s_mov_b64 s[100:101], exec
	s_and_b64 exec, exec, s[96:97]
	ds_write_b128 v181, v[10:13] offset:32768
	ds_write_b128 v182, v[14:17] offset:32768
	s_mov_b64 exec, s[100:101]
	s_waitcnt lgkmcnt(0)
	s_barrier
	ds_read_b32 v2, v173
	ds_read_b32 v3, v171
	s_waitcnt lgkmcnt(1)
	v_readfirstlane_b32 s43, v2
	s_waitcnt lgkmcnt(0)
	v_readfirstlane_b32 s42, v3
	v_lshlrev_b32_e32 v18, 4, v52
	v_mfma_f32_32x32x16_bf16 v[2:17], v[122:125], v[102:105], 0
	v_lshlrev_b32_e32 v64, 8, v53
	v_and_b32_e32 v65, 0x70, v18
	s_add_i32 s8, s12, 0
	v_bitop3_b32 v18, v98, v64, v65 bitop3:0xde
	v_and_b32_e32 v253, 8, v53
	v_lshlrev_b32_e32 v253, 4, v253
	v_add_u32_e32 v186, v253, v18
	ds_read_b128 v[56:59], v186 offset:32768
	ds_read_b128 v[60:63], v186 offset:40960
	v_lshlrev_b32_e32 v179, 2, v51
	s_waitcnt vmcnt(7) lgkmcnt(1)
	v_mfma_f32_32x32x16_bf16 v[18:33], v[56:59], v[118:121], v[2:17]
	v_or_b32_e32 v56, 32, v98
	v_bitop3_b32 v56, v56, v64, v65 bitop3:0xde
	v_add_u32_e32 v187, v253, v56
	s_waitcnt lgkmcnt(0)
	v_mfma_f32_32x32x16_bf16 v[2:17], v[60:63], v[118:121], v[2:17]
	ds_read_b128 v[56:59], v187 offset:32768
	ds_read_b128 v[60:63], v187 offset:40960
	s_waitcnt vmcnt(6) lgkmcnt(1)
	v_mfma_f32_32x32x16_bf16 v[18:33], v[56:59], v[114:117], v[18:33]
	v_or_b32_e32 v56, 64, v98
	v_bitop3_b32 v56, v56, v64, v65 bitop3:0xde
	v_add_u32_e32 v188, v253, v56
	s_waitcnt lgkmcnt(0)
	v_mfma_f32_32x32x16_bf16 v[2:17], v[60:63], v[114:117], v[2:17]
	ds_read_b128 v[56:59], v188 offset:32768
	ds_read_b128 v[60:63], v188 offset:40960
	s_waitcnt vmcnt(5) lgkmcnt(1)
	v_mfma_f32_32x32x16_bf16 v[18:33], v[56:59], v[110:113], v[18:33]
	v_or_b32_e32 v56, 0x60, v98
	v_bitop3_b32 v56, v56, v64, v65 bitop3:0xde
	v_add_u32_e32 v189, v253, v56
	s_waitcnt lgkmcnt(0)
	v_mfma_f32_32x32x16_bf16 v[2:17], v[60:63], v[110:113], v[2:17]
	ds_read_b128 v[56:59], v189 offset:32768
	ds_read_b128 v[60:63], v189 offset:40960
	s_waitcnt vmcnt(4) lgkmcnt(1)
	v_mfma_f32_32x32x16_bf16 v[18:33], v[56:59], v[106:109], v[18:33]
	v_add_u32_e32 v56, 0x9e, v185
	v_cmp_gt_u32_e64 s[8:9], s53, v56
	s_waitcnt lgkmcnt(0)
	v_mfma_f32_32x32x16_bf16 v[2:17], v[60:63], v[106:109], v[2:17]
	s_and_saveexec_b64 s[12:13], s[8:9]
	s_cbranch_execz .LBB0_338
	v_sub_u32_e32 v51, v179, v178
	v_lshl_add_u32 v51, v51, 2, s1
	ds_read2_b32 v[56:57], v51 offset0:240 offset1:241
	ds_read2_b32 v[58:59], v51 offset0:242 offset1:243
	ds_read2_b32 v[60:61], v51 offset0:248 offset1:249
	ds_read2_b32 v[62:63], v51 offset0:250 offset1:251
	ds_read2_b32 v[64:65], v51 offset0:224 offset1:225
	ds_read2_b32 v[66:67], v51 offset0:226 offset1:227
	ds_read2_b32 v[68:69], v51 offset0:232 offset1:233
	ds_read2_b32 v[70:71], v51 offset0:234 offset1:235
	s_waitcnt lgkmcnt(4)
	v_add_f32_e32 v32, v32, v62
	v_add_f32_e32 v33, v33, v63
	v_add_f32_e32 v30, v30, v60
	v_add_f32_e32 v31, v31, v61
	v_add_f32_e32 v28, v28, v58
	v_add_f32_e32 v29, v29, v59
	v_add_f32_e32 v26, v26, v56
	v_add_f32_e32 v27, v27, v57
	s_waitcnt lgkmcnt(0)
	v_add_f32_e32 v24, v24, v70
	v_add_f32_e32 v25, v25, v71
	v_add_f32_e32 v22, v22, v68
	v_add_f32_e32 v23, v23, v69
	v_add_f32_e32 v20, v20, v66
	v_add_f32_e32 v21, v21, v67
	v_add_f32_e32 v18, v18, v64
	v_add_f32_e32 v19, v19, v65
	v_add_u32_e32 v64, 0x400, v51
	v_add_u32_e32 v66, 0x408, v51
	v_add_u32_e32 v68, 0x420, v51
	v_add_u32_e32 v70, 0x428, v51
	v_add_u32_e32 v56, 0x440, v51
	v_add_u32_e32 v58, 0x448, v51
	v_add_u32_e32 v60, 0x460, v51
	v_add_u32_e32 v51, 0x468, v51
	ds_read2_b32 v[56:57], v56 offset1:1
	ds_read2_b32 v[58:59], v58 offset1:1
	ds_read2_b32 v[60:61], v60 offset1:1
	ds_read2_b32 v[62:63], v51 offset1:1
	ds_read2_b32 v[64:65], v64 offset1:1
	ds_read2_b32 v[66:67], v66 offset1:1
	ds_read2_b32 v[68:69], v68 offset1:1
	ds_read2_b32 v[70:71], v70 offset1:1
	s_waitcnt lgkmcnt(4)
	v_add_f32_e32 v16, v16, v62
	v_add_f32_e32 v17, v17, v63
	v_add_f32_e32 v14, v14, v60
	v_add_f32_e32 v15, v15, v61
	v_add_f32_e32 v12, v12, v58
	v_add_f32_e32 v13, v13, v59
	v_add_f32_e32 v10, v10, v56
	v_add_f32_e32 v11, v11, v57
	s_waitcnt lgkmcnt(0)
	v_add_f32_e32 v8, v8, v70
	v_add_f32_e32 v9, v9, v71
	v_add_f32_e32 v6, v6, v68
	v_add_f32_e32 v7, v7, v69
	v_add_f32_e32 v4, v4, v66
	v_add_f32_e32 v5, v5, v67
	v_add_f32_e32 v2, v2, v64
	v_add_f32_e32 v3, v3, v65
.LBB0_338:
	s_or_b64 exec, exec, s[12:13]
	v_mov_b32_e32 v51, s43
	v_mov_b32_e32 v56, s42
	v_cmp_gt_i32_e64 s[12:13], 0, v185
	s_nop 1
	v_max_f32_e32 v57, v18, v18
	v_mov_b32_e32 v190, 0
	v_cndmask_b32_e64 v51, v51, v56, s[12:13]
	v_cndmask_b32_e64 v56, v51, 0, s[8:9]
	v_max_f32_e32 v51, v19, v19
	v_max_f32_e32 v51, v57, v51
	v_max3_f32 v51, v51, v20, v21
	v_max3_f32 v51, v51, v22, v23
	v_max3_f32 v51, v51, v24, v25
	v_max3_f32 v51, v51, v26, v27
	v_max3_f32 v51, v51, v28, v29
	v_max3_f32 v51, v51, v30, v31
	v_max3_f32 v51, v51, v32, v33
	v_max3_f32 v51, v51, v2, v3
	v_max3_f32 v51, v51, v4, v5
	v_max3_f32 v51, v51, v6, v7
	v_max3_f32 v51, v51, v8, v9
	v_max3_f32 v51, v51, v10, v11
	v_max3_f32 v51, v51, v12, v13
	v_max3_f32 v51, v51, v14, v15
	v_max3_f32 v51, v51, v16, v17
	v_mov_b32_e32 v57, v51
	s_nop 1
	v_permlane32_swap_b32_e32 v51, v57
	v_max_f32_e32 v57, v57, v57
	v_max_f32_e32 v51, v51, v51
	v_max_f32_e32 v51, v51, v57
	v_add_f32_e32 v57, v56, v51
	v_sub_f32_e32 v191, s43, v57
	v_sub_f32_e32 v190, 0, v57
	v_sub_f32_e32 v192, s42, v57
	v_mov_b32_e32 v176, 0
	v_readfirstlane_b32 s98, v185
	s_mov_b32 s99, 64
	v_sub_f32_e32 v56, v56, v57
	v_add_f32_e32 v3, v3, v56
	v_add_f32_e32 v2, v2, v56
	v_add_f32_e32 v4, v4, v56
	v_exp_f32_e32 v196, v3
	v_lshlrev_b32_e32 v3, 4, v55
	s_xor_b64 s[42:43], s[2:3], -1
	v_exp_f32_e32 v195, v2
	v_exp_f32_e32 v197, v4
	v_lshlrev_b32_e32 v2, 3, v55
	v_and_b32_e32 v3, 0xc0, v3
	v_lshlrev_b32_e32 v4, 1, v55
	v_and_or_b32 v3, v2, 24, v3
	v_and_b32_e32 v4, 32, v4
	v_and_b32_e32 v2, 0x100, v2
	s_cmp_lg_u32 0, -1
	v_or3_b32 v2, v3, v4, v2
	s_cselect_b32 s2, 0, 0
	v_add_u32_e32 v180, s2, v2
	s_addk_i32 s2, 0x4000
	v_add_u32_e32 v177, s2, v2
	v_add_lshl_u32 v2, v185, v53, 2
	v_ashrrev_i32_e32 v51, 31, v50
	v_add_f32_e32 v18, v18, v56
	v_add_f32_e32 v19, v19, v56
	v_add_f32_e32 v20, v20, v56
	v_add_f32_e32 v21, v21, v56
	v_add_f32_e32 v22, v22, v56
	v_add_f32_e32 v23, v23, v56
	v_add_f32_e32 v24, v24, v56
	v_add_f32_e32 v25, v25, v56
	v_add_f32_e32 v26, v26, v56
	v_add_f32_e32 v27, v27, v56
	v_add_f32_e32 v28, v28, v56
	v_add_f32_e32 v29, v29, v56
	v_add_f32_e32 v30, v30, v56
	v_add_f32_e32 v31, v31, v56
	v_add_f32_e32 v32, v32, v56
	v_add_f32_e32 v33, v33, v56
	v_add_f32_e32 v5, v5, v56
	v_add_f32_e32 v6, v6, v56
	v_add_f32_e32 v7, v7, v56
	v_add_f32_e32 v8, v8, v56
	v_add_f32_e32 v9, v9, v56
	v_add_f32_e32 v10, v10, v56
	v_add_f32_e32 v11, v11, v56
	v_add_f32_e32 v12, v12, v56
	v_add_f32_e32 v13, v13, v56
	v_add_f32_e32 v14, v14, v56
	v_add_f32_e32 v15, v15, v56
	v_add_f32_e32 v16, v16, v56
	v_add_f32_e32 v17, v17, v56
	v_sub_u32_e32 v2, v98, v2
	s_add_i32 s2, 0, 0x10c80
	v_exp_f32_e32 v199, v18
	v_exp_f32_e32 v201, v19
	v_exp_f32_e32 v202, v20
	v_exp_f32_e32 v205, v21
	v_exp_f32_e32 v207, v22
	v_exp_f32_e32 v209, v23
	v_exp_f32_e32 v211, v24
	v_exp_f32_e32 v213, v25
	v_exp_f32_e32 v215, v26
	v_exp_f32_e32 v216, v27
	v_exp_f32_e32 v217, v28
	v_exp_f32_e32 v218, v29
	v_exp_f32_e32 v221, v30
	v_exp_f32_e32 v222, v31
	v_exp_f32_e32 v223, v32
	v_exp_f32_e32 v224, v33
	v_exp_f32_e32 v198, v5
	v_exp_f32_e32 v200, v6
	v_exp_f32_e32 v203, v7
	v_exp_f32_e32 v204, v8
	v_exp_f32_e32 v206, v9
	v_exp_f32_e32 v208, v10
	v_exp_f32_e32 v210, v11
	v_exp_f32_e32 v212, v12
	v_exp_f32_e32 v214, v13
	v_exp_f32_e32 v150, v14
	v_exp_f32_e32 v151, v15
	v_exp_f32_e32 v152, v16
	v_exp_f32_e32 v153, v17
	v_add_u32_e32 v194, s2, v2
	v_lshl_add_u64 v[2:3], s[30:31], 0, v[50:51]
	s_waitcnt vmcnt(0)
	v_mad_u64_u32 v[4:5], s[2:3], v2, s49, 0
	v_and_b32_e32 v2, 15, v52
	v_mad_i32_i24 v3, v3, s49, v5
	v_lshl_or_b32 v2, v2, 4, v4
	s_mov_b32 s82, 0
	s_waitcnt vmcnt(3)
	ds_write_b128 v183, v[34:37] offset:16384
	s_waitcnt vmcnt(2)
	ds_write_b128 v184, v[38:41] offset:16384
	s_waitcnt vmcnt(0)
	s_mov_b64 s[100:101], exec
	s_and_b64 exec, exec, s[96:97]
	ds_write_b128 v181, v[42:45] offset:49152
	ds_write_b128 v182, v[46:49] offset:49152
	s_mov_b64 exec, s[100:101]
	v_mov_b32_e32 v181, v180
	s_mov_b32 s54, 0
	s_movk_i32 s55, 0x4000
	s_mov_b32 s56, 0x12000
	v_sub_u32_e32 v193, s81, v54
	s_mov_b32 s83, 2
	v_lshl_add_u64 v[160:161], s[40:41], 0, v[2:3]
	s_and_b32 s100, s42, 0x80
	v_lshrrev_b32_e32 v2, 3, v52
	v_sub_u32_e32 v3, v2, v50
	v_mul_u32_u24_e32 v3, 0x2800, v3
	v_and_b32_e32 v4, 8, v52
	v_lshlrev_b32_e32 v4, 4, v4
	v_sub_u32_e32 v3, v3, v4
	v_add_u32_e32 v3, s100, v3
	v_readfirstlane_b32 s101, v50
	v_readfirstlane_b32 s12, v160
	v_readfirstlane_b32 s13, v161
	s_nop 1
	v_subrev_u32_e32 v4, s101, v50
	v_mul_u32_u24_e32 v4, 0x2800, v4
	v_and_b32_e32 v160, 15, v52
	v_lshl_add_u32 v160, v160, 4, v4
	v_add_u32_e32 v161, 0x50000, v160
	v_add_u32_e32 v252, v160, v3
	v_and_b32_e32 v3, 7, v52
	v_and_b32_e32 v4, 7, v2
	v_xor_b32_e32 v3, v3, v4
	v_lshlrev_b32_e32 v3, 4, v3
	v_lshl_or_b32 v235, v2, 8, v3
	v_and_b32_e32 v4, 8, v2
	v_lshl_or_b32 v235, v4, 4, v235
	v_mov_b32_e32 v2, 0
	v_mov_b32_e32 v3, v176
	v_mov_b32_e32 v4, v176
	v_mov_b32_e32 v5, v176
	v_mov_b32_e32 v6, v176
	v_mov_b32_e32 v7, v176
	v_mov_b32_e32 v8, v176
	v_mov_b32_e32 v9, v176
	v_mov_b32_e32 v10, v176
	v_mov_b32_e32 v11, v176
	v_mov_b32_e32 v12, v176
	v_mov_b32_e32 v13, v176
	v_mov_b32_e32 v14, v176
	v_mov_b32_e32 v15, v176
	v_mov_b32_e32 v16, v176
	v_mov_b32_e32 v17, v176
	v_mov_b32_e32 v18, 0
	v_mov_b32_e32 v19, v176
	v_mov_b32_e32 v20, v176
	v_mov_b32_e32 v21, v176
	v_mov_b32_e32 v22, v176
	v_mov_b32_e32 v23, v176
	v_mov_b32_e32 v24, v176
	v_mov_b32_e32 v25, v176
	v_mov_b32_e32 v26, v176
	v_mov_b32_e32 v27, v176
	v_mov_b32_e32 v28, v176
	v_mov_b32_e32 v29, v176
	v_mov_b32_e32 v30, v176
	v_mov_b32_e32 v31, v176
	v_mov_b32_e32 v32, v176
	v_mov_b32_e32 v33, v176
	v_mov_b32_e32 v34, 0
	v_mov_b32_e32 v35, v176
	v_mov_b32_e32 v36, v176
	v_mov_b32_e32 v37, v176
	v_mov_b32_e32 v38, v176
	v_mov_b32_e32 v39, v176
	v_mov_b32_e32 v40, v176
	v_mov_b32_e32 v41, v176
	v_mov_b32_e32 v42, v176
	v_mov_b32_e32 v43, v176
	v_mov_b32_e32 v44, v176
	v_mov_b32_e32 v45, v176
	v_mov_b32_e32 v46, v176
	v_mov_b32_e32 v47, v176
	v_mov_b32_e32 v48, v176
	v_mov_b32_e32 v49, v176
	v_mov_b32_e32 v50, 0
	v_mov_b32_e32 v51, v176
	v_mov_b32_e32 v52, v176
	v_mov_b32_e32 v53, v176
	v_mov_b32_e32 v54, v176
	v_mov_b32_e32 v55, v176
	v_mov_b32_e32 v56, v176
	v_mov_b32_e32 v57, v176
	v_mov_b32_e32 v58, v176
	v_mov_b32_e32 v59, v176
	v_mov_b32_e32 v60, v176
	v_mov_b32_e32 v61, v176
	v_mov_b32_e32 v62, v176
	v_mov_b32_e32 v63, v176
	v_mov_b32_e32 v64, v176
	v_mov_b32_e32 v65, v176
	s_waitcnt lgkmcnt(0)
	s_barrier
	s_branch .LBB0_346
